# stack9 with the attention-phase static priority on waves 0-3 instead of 4-7 (per-half A/B of the priority raise)
# baseline (speedup 1.0000x reference)
.LBB8_541:
	v_writelane_b32 v254, s26, 59
	s_cmp_lt_i32 s92, 5
	s_cselect_b64 s[4:5], -1, 0
	v_writelane_b32 v254, s27, 60
	s_nop 0
	v_readlane_b32 s6, v254, 2
	v_readlane_b32 s7, v254, 3
	s_add_u32 s26, s6, 0xc0000
	s_addc_u32 s27, s7, 0
	s_add_u32 s70, s6, 0x4800000
	s_addc_u32 s71, s7, 0
	s_and_b64 s[0:1], s[4:5], s[0:1]
	v_writelane_b32 v254, s0, 61
	s_andn2_b64 vcc, exec, s[0:1]
	s_nop 0
	v_writelane_b32 v254, s1, 62
	s_cbranch_vccnz .LBB8_774
	s_cmpk_lt_u32 s96, 0x100
	s_cbranch_scc0 .Lq_p4_noprio
	s_setprio 1
